# baseline (speedup 1.0000x reference)
; __device__ __forceinline__ int opaque_tid(int wid_s) { int l = __builtin_amdgcn_mbcnt_hi(~0u, __builtin_amdgcn_mbcnt_lo(~0u, 0u)); asm volatile("" : "+v"(l)); return (wid_s << 6) | l; }
; __device__ __forceinline__ void phase_fix(int wid_s, const float* BND, bf16_t* ACT) {
;     const int tid = opaque_tid(wid_s);
;     for (int g = blockIdx.x * NTHREADS + tid; g < NSLAB * 2 * (DFF / 4); g += gridDim.x * NTHREADS) {
;         const int r = g / (DFF / 4), f = (g % (DFF / 4)) * 4, s = r >> 1, fr = r & 1;
;         if ((s & 31) == 0) continue;
;         const size_t o0 = ((size_t)s * 2 + fr) * NUP, o1 = ((size_t)(NSLAB + s) * 2 + fr) * NUP;
;         const bf16_t* B16 = (const bf16_t*)BND;
;         const u32x2 a0 = *(const u32x2*)(B16 + o0 + f), a1 = *(const u32x2*)(B16 + o1 + f), g0 = *(const u32x2*)(B16 + o0 + DFF + f), g1 = *(const u32x2*)(B16 + o1 + DFF + f);
.LBB0_857:
	s_andn2_b64 vcc, exec, s[0:1]
	s_cbranch_vccnz .LBB0_909
	s_mov_b64 s[2:3], s[72:73]
	s_mov_b64 s[4:5], s[72:73]
	v_mov_b32_e32 v0, v240
	v_readlane_b32 s0, v253, 37
	s_nop 1
	v_or_b32_e32 v0, s0, v0
	v_readlane_b32 s0, v253, 44
	s_nop 1
	v_add_u32_e32 v3, s0, v0
	s_mov_b32 s0, 0x56000
	v_cmp_gt_i32_e32 vcc, s0, v3
	s_and_saveexec_b64 s[0:1], vcc
	s_cbranch_execz .LBB0_863
	s_add_u32 s2, s2, 0x2a400000
	s_addc_u32 s3, s3, 0
	s_add_u32 s4, s4, 0x24e00000
	s_addc_u32 s5, s5, 0
	s_waitcnt vmcnt(0)
	s_mov_b64 s[18:19], exec
	s_mov_b32 s8, 0x2fa0be83
	s_mov_b32 s9, 0x56000
	v_mov_b32_e32 v20, v3
	v_mul_hi_i32 v21, v20, s8
	v_ashrrev_i32_e32 v21, 8, v21
	v_cmp_gt_i32_e64 s[20:21], s9, v20
	v_and_b32_e32 v28, 62, v21
	v_cmp_ne_u32_e64 s[14:15], 0, v28
	v_mul_u32_u24_e32 v28, 0x560, v21
	v_sub_u32_e32 v28, v20, v28
	v_lshlrev_b32_e32 v22, 3, v28
	s_and_b64 s[20:21], s[20:21], s[14:15]
	v_mul_u32_u24_e32 v23, 0x5600, v21
	v_add_u32_e32 v23, v23, v22
	v_add_u32_e32 v24, 0x2b00, v23
	v_add_u32_e32 v25, 0x560000, v23
	v_add_u32_e32 v26, 0x2b00, v25
	v_lshlrev_b32_e32 v27, 5, v21
	v_and_b32_e32 v27, 0xffc0, v27
	v_and_b32_e32 v28, 1, v21
	v_or_b32_e32 v27, v27, v28
	v_mul_u32_u24_e32 v27, 0x2b00, v27
	v_add_u32_e32 v27, v27, v22
	s_mov_b64 exec, s[20:21]
	global_load_dwordx2 v[30:31], v23, s[2:3]
	global_load_dwordx2 v[32:33], v25, s[2:3]
	global_load_dwordx2 v[34:35], v24, s[2:3]
	global_load_dwordx2 v[36:37], v26, s[2:3]
	s_mov_b64 exec, s[18:19]
	v_add_u32_e32 v40, s78, v20
	v_mul_hi_i32 v41, v40, s8
	v_ashrrev_i32_e32 v41, 8, v41
	v_cmp_gt_i32_e64 s[22:23], s9, v40
	v_and_b32_e32 v48, 62, v41
	v_cmp_ne_u32_e64 s[14:15], 0, v48
	v_mul_u32_u24_e32 v48, 0x560, v41
	v_sub_u32_e32 v48, v40, v48
	v_lshlrev_b32_e32 v42, 3, v48
	s_and_b64 s[22:23], s[22:23], s[14:15]
	v_mul_u32_u24_e32 v43, 0x5600, v41
	v_add_u32_e32 v43, v43, v42
	v_add_u32_e32 v44, 0x2b00, v43
	v_add_u32_e32 v45, 0x560000, v43
	v_add_u32_e32 v46, 0x2b00, v45
	v_lshlrev_b32_e32 v47, 5, v41
	v_and_b32_e32 v47, 0xffc0, v47
	v_and_b32_e32 v48, 1, v41
	v_or_b32_e32 v47, v47, v48
	v_mul_u32_u24_e32 v47, 0x2b00, v47
	v_add_u32_e32 v47, v47, v42
	s_mov_b64 exec, s[22:23]
	global_load_dwordx2 v[50:51], v43, s[2:3]
	global_load_dwordx2 v[52:53], v45, s[2:3]
	global_load_dwordx2 v[54:55], v44, s[2:3]
	global_load_dwordx2 v[56:57], v46, s[2:3]
	s_mov_b64 exec, s[18:19]
	v_add_u32_e32 v60, s78, v40
	v_mul_hi_i32 v61, v60, s8
	v_ashrrev_i32_e32 v61, 8, v61
	v_cmp_gt_i32_e64 s[24:25], s9, v60
	v_and_b32_e32 v68, 62, v61
	v_cmp_ne_u32_e64 s[14:15], 0, v68
	v_mul_u32_u24_e32 v68, 0x560, v61
	v_sub_u32_e32 v68, v60, v68
	v_lshlrev_b32_e32 v62, 3, v68
	s_and_b64 s[24:25], s[24:25], s[14:15]
	v_mul_u32_u24_e32 v63, 0x5600, v61
	v_add_u32_e32 v63, v63, v62
	v_add_u32_e32 v64, 0x2b00, v63
	v_add_u32_e32 v65, 0x560000, v63
	v_add_u32_e32 v66, 0x2b00, v65
	v_lshlrev_b32_e32 v67, 5, v61
	v_and_b32_e32 v67, 0xffc0, v67
	v_and_b32_e32 v68, 1, v61
	v_or_b32_e32 v67, v67, v68
	v_mul_u32_u24_e32 v67, 0x2b00, v67
	v_add_u32_e32 v67, v67, v62
	s_mov_b64 exec, s[24:25]
	global_load_dwordx2 v[70:71], v63, s[2:3]
	global_load_dwordx2 v[72:73], v65, s[2:3]
	global_load_dwordx2 v[74:75], v64, s[2:3]
	global_load_dwordx2 v[76:77], v66, s[2:3]
	s_mov_b64 exec, s[18:19]
	s_waitcnt vmcnt(0)
; __device__ __forceinline__ float h2f(unsigned h) { float r; asm volatile("v_cvt_f32_f16 %0, %1" : "=v"(r) : "v"(h)); return r; }
; __device__ __forceinline__ u32x2 pack4(f32x4 v) { u32x2 r; r.x = cvt_pk_bf16(v[0], v[1]); r.y = cvt_pk_bf16(v[2], v[3]); return r; }
; __device__ __forceinline__ float sigmoidf_(float x) { return __builtin_amdgcn_rcpf(1.0f + __expf(-x)); }
; __device__ __forceinline__ void phase_fix(int wid_s, const float* BND, bf16_t* ACT) {
;     ...
;         const f32x4 cv = (f32x4){h2f(a0.x), h2f(a0.x >> 16), h2f(a0.y), h2f(a0.y >> 16)} + (f32x4){h2f(a1.x), h2f(a1.x >> 16), h2f(a1.y), h2f(a1.y >> 16)};
;         const f32x4 cgt = (f32x4){h2f(g0.x), h2f(g0.x >> 16), h2f(g0.y), h2f(g0.y >> 16)} + (f32x4){h2f(g1.x), h2f(g1.x >> 16), h2f(g1.y), h2f(g1.y >> 16)};
;         f32x4 a;
; #pragma unroll
;         for (int j = 0; j < 4; ++j) a[j] = cv[j] * cgt[j] * sigmoidf_(cgt[j]);
;         *(u32x2*)(ACT + (size_t)(s * 64 + fr) * DFF + f) = pack4(a);
	s_mov_b64 exec, s[20:21]
	v_lshrrev_b32_e32 v106, 16, v30
	v_lshrrev_b32_e32 v107, 16, v31
	v_cvt_f32_f16_e32 v90, v30
	v_cvt_f32_f16_e32 v92, v31
	v_cvt_f32_f16_e32 v91, v106
	v_cvt_f32_f16_e32 v93, v107
	v_lshrrev_b32_e32 v106, 16, v32
	v_lshrrev_b32_e32 v107, 16, v33
	v_cvt_f32_f16_e32 v94, v32
	v_cvt_f32_f16_e32 v96, v33
	v_cvt_f32_f16_e32 v95, v106
	v_cvt_f32_f16_e32 v97, v107
	v_lshrrev_b32_e32 v106, 16, v34
	v_lshrrev_b32_e32 v107, 16, v35
	v_cvt_f32_f16_e32 v98, v34
	v_cvt_f32_f16_e32 v100, v35
	v_cvt_f32_f16_e32 v99, v106
	v_cvt_f32_f16_e32 v101, v107
	v_lshrrev_b32_e32 v106, 16, v36
	v_lshrrev_b32_e32 v107, 16, v37
	v_cvt_f32_f16_e32 v102, v36
	v_cvt_f32_f16_e32 v104, v37
	v_cvt_f32_f16_e32 v103, v106
	v_cvt_f32_f16_e32 v105, v107
	v_add_f32_e32 v90, v90, v94
	v_add_f32_e32 v91, v91, v95
	v_add_f32_e32 v92, v92, v96
	v_add_f32_e32 v93, v93, v97
	v_add_f32_e32 v98, v98, v102
	v_add_f32_e32 v99, v99, v103
	v_add_f32_e32 v100, v100, v104
	v_add_f32_e32 v101, v101, v105
	v_mul_f32_e32 v90, v90, v98
	v_mul_f32_e32 v91, v91, v99
	v_mul_f32_e32 v92, v92, v100
	v_mul_f32_e32 v93, v93, v101
	v_mul_f32_e32 v98, 0xbfb8aa3b, v98
	v_mul_f32_e32 v99, 0xbfb8aa3b, v99
	v_mul_f32_e32 v100, 0xbfb8aa3b, v100
	v_mul_f32_e32 v101, 0xbfb8aa3b, v101
	v_exp_f32_e32 v98, v98
	v_exp_f32_e32 v99, v99
	v_exp_f32_e32 v100, v100
	v_exp_f32_e32 v101, v101
	v_add_f32_e32 v98, 1.0, v98
	v_add_f32_e32 v99, 1.0, v99
	v_add_f32_e32 v100, 1.0, v100
	v_add_f32_e32 v101, 1.0, v101
	v_rcp_f32_e32 v98, v98
	v_rcp_f32_e32 v99, v99
	v_rcp_f32_e32 v100, v100
	v_rcp_f32_e32 v101, v101
	v_mul_f32_e32 v90, v90, v98
	v_mul_f32_e32 v91, v91, v99
	v_mul_f32_e32 v92, v92, v100
	v_mul_f32_e32 v93, v93, v101
	v_cvt_pkrtz_f16_f32 v108, v90, v91
	v_cvt_pkrtz_f16_f32 v109, v92, v93
	global_store_dwordx2 v27, v[108:109], s[4:5]
	s_mov_b64 exec, s[18:19]
	s_nop 1
	s_mov_b64 exec, s[22:23]
	v_lshrrev_b32_e32 v106, 16, v50
	v_lshrrev_b32_e32 v107, 16, v51
	v_cvt_f32_f16_e32 v90, v50
	v_cvt_f32_f16_e32 v92, v51
	v_cvt_f32_f16_e32 v91, v106
	v_cvt_f32_f16_e32 v93, v107
	v_lshrrev_b32_e32 v106, 16, v52
	v_lshrrev_b32_e32 v107, 16, v53
	v_cvt_f32_f16_e32 v94, v52
	v_cvt_f32_f16_e32 v96, v53
	v_cvt_f32_f16_e32 v95, v106
	v_cvt_f32_f16_e32 v97, v107
	v_lshrrev_b32_e32 v106, 16, v54
	v_lshrrev_b32_e32 v107, 16, v55
	v_cvt_f32_f16_e32 v98, v54
	v_cvt_f32_f16_e32 v100, v55
	v_cvt_f32_f16_e32 v99, v106
	v_cvt_f32_f16_e32 v101, v107
	v_lshrrev_b32_e32 v106, 16, v56
	v_lshrrev_b32_e32 v107, 16, v57
	v_cvt_f32_f16_e32 v102, v56
	v_cvt_f32_f16_e32 v104, v57
	v_cvt_f32_f16_e32 v103, v106
	v_cvt_f32_f16_e32 v105, v107
	v_add_f32_e32 v90, v90, v94
	v_add_f32_e32 v91, v91, v95
	v_add_f32_e32 v92, v92, v96
	v_add_f32_e32 v93, v93, v97
	v_add_f32_e32 v98, v98, v102
	v_add_f32_e32 v99, v99, v103
	v_add_f32_e32 v100, v100, v104
	v_add_f32_e32 v101, v101, v105
	v_mul_f32_e32 v90, v90, v98
	v_mul_f32_e32 v91, v91, v99
	v_mul_f32_e32 v92, v92, v100
	v_mul_f32_e32 v93, v93, v101
	v_mul_f32_e32 v98, 0xbfb8aa3b, v98
	v_mul_f32_e32 v99, 0xbfb8aa3b, v99
	v_mul_f32_e32 v100, 0xbfb8aa3b, v100
	v_mul_f32_e32 v101, 0xbfb8aa3b, v101
	v_exp_f32_e32 v98, v98
	v_exp_f32_e32 v99, v99
	v_exp_f32_e32 v100, v100
	v_exp_f32_e32 v101, v101
	v_add_f32_e32 v98, 1.0, v98
	v_add_f32_e32 v99, 1.0, v99
	v_add_f32_e32 v100, 1.0, v100
	v_add_f32_e32 v101, 1.0, v101
	v_rcp_f32_e32 v98, v98
	v_rcp_f32_e32 v99, v99
	v_rcp_f32_e32 v100, v100
	v_rcp_f32_e32 v101, v101
	v_mul_f32_e32 v90, v90, v98
	v_mul_f32_e32 v91, v91, v99
	v_mul_f32_e32 v92, v92, v100
	v_mul_f32_e32 v93, v93, v101
	v_cvt_pkrtz_f16_f32 v108, v90, v91
	v_cvt_pkrtz_f16_f32 v109, v92, v93
	global_store_dwordx2 v47, v[108:109], s[4:5]
	s_mov_b64 exec, s[18:19]
	s_nop 1
	s_mov_b64 exec, s[24:25]
	v_lshrrev_b32_e32 v106, 16, v70
	v_lshrrev_b32_e32 v107, 16, v71
	v_cvt_f32_f16_e32 v90, v70
	v_cvt_f32_f16_e32 v92, v71
	v_cvt_f32_f16_e32 v91, v106
	v_cvt_f32_f16_e32 v93, v107
	v_lshrrev_b32_e32 v106, 16, v72
	v_lshrrev_b32_e32 v107, 16, v73
	v_cvt_f32_f16_e32 v94, v72
	v_cvt_f32_f16_e32 v96, v73
	v_cvt_f32_f16_e32 v95, v106
	v_cvt_f32_f16_e32 v97, v107
	v_lshrrev_b32_e32 v106, 16, v74
	v_lshrrev_b32_e32 v107, 16, v75
	v_cvt_f32_f16_e32 v98, v74
	v_cvt_f32_f16_e32 v100, v75
	v_cvt_f32_f16_e32 v99, v106
	v_cvt_f32_f16_e32 v101, v107
	v_lshrrev_b32_e32 v106, 16, v76
	v_lshrrev_b32_e32 v107, 16, v77
	v_cvt_f32_f16_e32 v102, v76
	v_cvt_f32_f16_e32 v104, v77
	v_cvt_f32_f16_e32 v103, v106
	v_cvt_f32_f16_e32 v105, v107
	v_add_f32_e32 v90, v90, v94
	v_add_f32_e32 v91, v91, v95
	v_add_f32_e32 v92, v92, v96
	v_add_f32_e32 v93, v93, v97
	v_add_f32_e32 v98, v98, v102
	v_add_f32_e32 v99, v99, v103
	v_add_f32_e32 v100, v100, v104
	v_add_f32_e32 v101, v101, v105
	v_mul_f32_e32 v90, v90, v98
	v_mul_f32_e32 v91, v91, v99
	v_mul_f32_e32 v92, v92, v100
	v_mul_f32_e32 v93, v93, v101
	v_mul_f32_e32 v98, 0xbfb8aa3b, v98
	v_mul_f32_e32 v99, 0xbfb8aa3b, v99
	v_mul_f32_e32 v100, 0xbfb8aa3b, v100
	v_mul_f32_e32 v101, 0xbfb8aa3b, v101
	v_exp_f32_e32 v98, v98
	v_exp_f32_e32 v99, v99
	v_exp_f32_e32 v100, v100
	v_exp_f32_e32 v101, v101
	v_add_f32_e32 v98, 1.0, v98
	v_add_f32_e32 v99, 1.0, v99
	v_add_f32_e32 v100, 1.0, v100
	v_add_f32_e32 v101, 1.0, v101
	v_rcp_f32_e32 v98, v98
	v_rcp_f32_e32 v99, v99
	v_rcp_f32_e32 v100, v100
	v_rcp_f32_e32 v101, v101
	v_mul_f32_e32 v90, v90, v98
	v_mul_f32_e32 v91, v91, v99
	v_mul_f32_e32 v92, v92, v100
	v_mul_f32_e32 v93, v93, v101
	v_cvt_pkrtz_f16_f32 v108, v90, v91
	v_cvt_pkrtz_f16_f32 v109, v92, v93
	global_store_dwordx2 v67, v[108:109], s[4:5]
	s_mov_b64 exec, s[18:19]
	s_nop 1
